# G1+A1 + phase-13 nt loads/stores + static setprio 1 for waves 4-7 during attention
# baseline (speedup 1.0000x reference)
; __device__ __forceinline__ int crow(int r, int hi) { return (r & 3) + 8 * (r >> 2) + 4 * hi; }
; __device__ __forceinline__ void attn_unit256q(const bf16* __restrict__ Qb, const unsigned char* __restrict__ Kc, const unsigned char* __restrict__ Kl, const float* __restrict__ Sc, const float* __restrict__ Sl, ...
;     ...
;     const float inv = mx > 0.f ? 127.f / mx : 0.f, qs = mx * (1.f / 127.f);
;     Cq = C * qs; thrq = mx > 0.f ? THR / (SCALE * qs) : 3.0e38f;
;     ...
; #pragma unroll
;     for (int d0 = 0; d0 < 4; ++d0) { qr[d0][0] = (int)Q5_Q2(qa[d0].x, qa[d0].y); qr[d0][1] = (int)Q5_Q2(qa[d0].z, qa[d0].w); qr[d0][2] = (int)Q5_Q2(qb[d0].x, qb[d0].y); qr[d0][3] = (int)Q5_Q2(qb[d0].z, qb[d0].w); }
;     ...
;   }
;   { glds16((const char*)Kc + koff, (unsigned)__builtin_amdgcn_readfirstlane(kdst));
; #pragma unroll
;     for (int i = 0; i < 4; ++i) glds16((const char*)Vc + voff[i], (unsigned)__builtin_amdgcn_readfirstlane(vdst + i * 1024)); }
;   const int kx = (r32 & 7) << 4;
;   const lds_cptr kp0 = shm3 + LDS_K + r32 * 128, vp0 = shm3 + LDS_V + v_rd_base(lane);
;   float ksn0 = Sc[0], ksn1 = Sc[1];
;   constexpr float BIAS = 12582912.f;
;   i32x16 bini;
; #pragma unroll
;   for (int r = 0; r < 16; ++r) bini[r] = 0x4B400000;
;   asm volatile("" : "+v"(bini));
; __global__ void __launch_bounds__(NWAVES * 64, 2) fwd_kernel(Args args) {
;     ...
;         xcd_barrier(bar);
;         float* sml = (float*)((char*)lds + ATT_SML_OFF);
;         for (int i = 0;; ++i) {
;             const long Lu = (long)i * G + bx; if (Lu >= 2176) break;
;             int b, h, n, qrow0, seq;
;             if (Lu < 2048) { const int xcd = (int)(Lu & 7), k = (int)(Lu >> 3), bh = xcd * 8 + (k >> 5), r = k & 31; b = bh >> 4; h = bh & 15; n = r >> 4; qrow0 = b * 4096 + (r & 15) * 256; seq = 4352; }
;             else { const int e = (int)Lu - 2048; b = e >> 5; h = (e >> 1) & 15; n = e & 1; qrow0 = MLAT + b * 256; seq = 256; }
;             const size_t hm = (size_t)(h * 2 + n) * 17408, qk0 = hm * 128, v0 = (size_t)h * 17408 * 256; const size_t crow = MLAT + b * 256, lrow = b * 4096;
;             att2::attn_unit256q(QH + qk0 + (size_t)qrow0 * 128, K8 + (hm + crow) * 128, K8 + (hm + lrow) * 128, KSC + (hm + crow) / 32, KSC + (hm + lrow) / 32, VH + v0 + crow * 256, VH + v0 + lrow * 256,
;                                 OB + (size_t)qrow0 * 8192 + n * 4096 + h * 256, seq, (char*)lds + RING_OFF, sml);
.LBB0_527:
	s_or_b64 exec, exec, s[0:1]
	s_add_u32 s22, s30, 0x1ca00000
	v_readlane_b32 s0, v243, 50
	s_addc_u32 s23, s31, 0
	s_ashr_i32 s24, s33, 31
	s_ashr_i32 s25, s0, 31
	s_mov_b32 s5, 0
	v_mov_b64_e32 v[198:199], 0x87f
	v_mov_b32_e32 v201, 0
	s_mov_b32 s26, 0x41000000
	s_mov_b32 s27, 0x42fe0000
	s_mov_b32 s34, 0x40c0c00
	s_mov_b64 s[6:7], 0x80
	s_mov_b64 s[8:9], 0x100
	s_mov_b64 s[10:11], 0x180
	v_mov_b64_e32 v[202:203], 0x7ff
	v_mov_b32_e32 v217, 0x7ffff3
	s_waitcnt lgkmcnt(0)
	v_mov_b32_e32 v2, 0x4b400000
	v_readlane_b32 s98, v243, 0
	s_nop 3
	s_cmp_ge_u32 s98, 4
	s_cbranch_scc0 .Lprio_skip
	s_setprio 1
.Lprio_skip:
	s_mov_b32 s35, 0
	s_barrier
	s_branch .LBB0_530

; __device__ __forceinline__ int crow(int r, int hi) { return (r & 3) + 8 * (r >> 2) + 4 * hi; }
; __device__ __forceinline__ int crow(int r, int hi) { return (r & 3) + 8 * (r >> 2) + 4 * hi; }
; __global__ void __launch_bounds__(NWAVES * 64, 2) fwd_kernel(Args args) {
;     ...
;         for (int i = 0;; ++i) {
;             const long Lu = (long)i * G + bx; if (Lu >= 2176) break;
;             int b, h, n, qrow0, seq;
;             if (Lu < 2048) { const int xcd = (int)(Lu & 7), k = (int)(Lu >> 3), bh = xcd * 8 + (k >> 5), r = k & 31; b = bh >> 4; h = bh & 15; n = r >> 4; qrow0 = b * 4096 + (r & 15) * 256; seq = 4352; }
;             else { const int e = (int)Lu - 2048; b = e >> 5; h = (e >> 1) & 15; n = e & 1; qrow0 = MLAT + b * 256; seq = 256; }
;             const size_t hm = (size_t)(h * 2 + n) * 17408, qk0 = hm * 128, v0 = (size_t)h * 17408 * 256; const size_t crow = MLAT + b * 256, lrow = b * 4096;
;             att2::attn_unit256q(QH + qk0 + (size_t)qrow0 * 128, K8 + (hm + crow) * 128, K8 + (hm + lrow) * 128, KSC + (hm + crow) / 32, KSC + (hm + lrow) / 32, VH + v0 + crow * 256, VH + v0 + lrow * 256,
;                                 OB + (size_t)qrow0 * 8192 + n * 4096 + h * 256, seq, (char*)lds + RING_OFF, sml);
;         }
;         __syncthreads();
.LBB0_559:
	s_setprio 0
	s_waitcnt vmcnt(63) expcnt(7) lgkmcnt(15)
	s_barrier

; __device__ __forceinline__ float bflo(unsigned w) { return __uint_as_float(w << 16); }
; __device__ __forceinline__ float bfhi(unsigned w) { return __uint_as_float(w & 0xffff0000u); }
; #define GAS __attribute__((address_space(1)))
; #define LAS __attribute__((address_space(3)))
; __global__ void __launch_bounds__(NWAVES * 64, 2) fwd_kernel(Args args) {
;     ...
;         if (bq < 4) for (int r = wl * NWAVES + wave; r < SEQL; r += wgb * NWAVES) {
;             const int row = bq * SEQL + r; const bf16* op = OUT1 + (size_t)row * DM; float* xo = args.out + (size_t)row * DM;
;             unsigned vbase = (unsigned)lane * 16u; asm volatile("" : "+v"(vbase));
;             const LAS f32x4* Vg_ = (const LAS f32x4*)(L + vbase);
;             v2u ov[16]; float ss = 0.f;
; #pragma unroll
;             for (int j = 0; j < 16; ++j) { ov[j] = ((const GAS v2u*)op)[lane + 64 * j]; const float a = pg8::bflo(ov[j].x), b = pg8::bfhi(ov[j].x), c = pg8::bflo(ov[j].y), d = pg8::bfhi(ov[j].y); ss += (a * a + b * b) + (c * c + d * d); }
;             v2u xv[16]; const bf16* x1p = X1B + (size_t)row * DM;
; #pragma unroll
;             for (int j = 0; j < 16; ++j) xv[j] = ((const GAS v2u*)x1p)[lane + 64 * j];
;             const float rstd = __builtin_amdgcn_rsqf(wave_sum(ss) * (1.f / DM) + EPS);
; #pragma unroll
;             for (int j = 0; j < 16; ++j) { const f32x4 o4 = {pg8::bflo(ov[j].x), pg8::bfhi(ov[j].x), pg8::bflo(ov[j].y), pg8::bfhi(ov[j].y)};
;                 const f32x4 x4 = {pg8::bflo(xv[j].x), pg8::bfhi(xv[j].x), pg8::bflo(xv[j].y), pg8::bfhi(xv[j].y)};
;                 ((GAS f32x4*)xo)[lane + 64 * j] = x4 + Vg_[64 * j] * (o4 * rstd); if ((j & 3) == 3) __builtin_amdgcn_sched_barrier(0); }
;         }
.LBB0_1335:
	s_add_i32 s0, s7, s6
	s_ashr_i32 s1, s0, 31
	s_lshl_b64 s[2:3], s[0:1], 13
	s_add_u32 s4, s68, s2
	s_addc_u32 s5, s69, s3
	v_mov_b32_e32 v30, v84
	global_load_dwordx2 v[2:3], v85, s[4:5] nt
	global_load_dwordx2 v[0:1], v85, s[4:5] offset:512 nt
	global_load_dwordx2 v[4:5], v85, s[4:5] offset:1024 nt
	global_load_dwordx2 v[6:7], v85, s[4:5] offset:1536 nt
	global_load_dwordx2 v[8:9], v85, s[4:5] offset:2048 nt
	global_load_dwordx2 v[10:11], v85, s[4:5] offset:2560 nt
	global_load_dwordx2 v[12:13], v85, s[4:5] offset:3072 nt
	global_load_dwordx2 v[14:15], v85, s[4:5] offset:3584 nt
	global_load_dwordx2 v[16:17], v86, s[4:5] nt
	global_load_dwordx2 v[18:19], v87, s[4:5] nt
	global_load_dwordx2 v[20:21], v88, s[4:5] nt
	global_load_dwordx2 v[24:25], v89, s[4:5] nt
	global_load_dwordx2 v[108:109], v90, s[4:5] nt
	global_load_dwordx2 v[110:111], v91, s[4:5] nt
	global_load_dwordx2 v[112:113], v92, s[4:5] nt
	global_load_dwordx2 v[114:115], v93, s[4:5] nt
	s_lshl_b64 s[0:1], s[0:1], 14
	s_add_u32 s0, s66, s0
	s_addc_u32 s1, s67, s1
	s_add_u32 s2, s10, s2
	s_addc_u32 s3, s11, s3
	global_load_dwordx2 v[22:23], v87, s[2:3] nt
	global_load_dwordx2 v[36:37], v86, s[2:3] nt
	global_load_dwordx2 v[28:29], v89, s[2:3] nt
	global_load_dwordx2 v[44:45], v88, s[2:3] nt
	s_waitcnt vmcnt(19)
	v_and_b32_e32 v117, 0xffff0000, v3
	s_waitcnt vmcnt(18)
	v_and_b32_e32 v81, 0xffff0000, v1
	v_and_b32_e32 v80, 0xffff0000, v0
	v_lshlrev_b32_e32 v83, 16, v1
	v_lshlrev_b32_e32 v82, 16, v0
	s_waitcnt vmcnt(17)
	v_lshlrev_b32_e32 v76, 16, v4
	v_and_b32_e32 v77, 0xffff0000, v4
	v_lshlrev_b32_e32 v78, 16, v5
	s_waitcnt vmcnt(11)
	v_and_b32_e32 v51, 0xffff0000, v17
	v_and_b32_e32 v50, 0xffff0000, v16
	v_and_b32_e32 v79, 0xffff0000, v5
	v_and_b32_e32 v69, 0xffff0000, v9
	v_and_b32_e32 v68, 0xffff0000, v8
	v_lshlrev_b32_e32 v63, 16, v11
	v_lshlrev_b32_e32 v62, 16, v10
	v_and_b32_e32 v65, 0xffff0000, v11
	v_and_b32_e32 v64, 0xffff0000, v10
	v_lshlrev_b32_e32 v49, 16, v17
	v_lshlrev_b32_e32 v48, 16, v16
	v_pk_mul_f32 v[4:5], v[80:81], v[80:81]
	v_pk_mul_f32 v[10:11], v[50:51], v[50:51]
	v_lshlrev_b32_e32 v116, 16, v3
	v_lshlrev_b32_e32 v75, 16, v6
	v_and_b32_e32 v73, 0xffff0000, v6
	v_lshlrev_b32_e32 v70, 16, v7
	v_and_b32_e32 v71, 0xffff0000, v7
	v_lshlrev_b32_e32 v67, 16, v9
	v_lshlrev_b32_e32 v66, 16, v8
	v_mul_f32_e32 v0, v117, v117
	v_pk_mul_f32 v[6:7], v[68:69], v[68:69]
	v_pk_fma_f32 v[120:121], v[82:83], v[82:83], v[4:5]
	v_pk_fma_f32 v[4:5], v[48:49], v[48:49], v[10:11]
	v_pk_fma_f32 v[118:119], v[116:117], v[116:117], v[0:1] op_sel_hi:[1,1,0]
	v_pk_fma_f32 v[0:1], v[66:67], v[66:67], v[6:7]
	v_pk_add_f32 v[128:129], v[4:5], v[4:5] op_sel:[0,1] op_sel_hi:[1,0]
	s_waitcnt vmcnt(4)
	v_lshlrev_b32_e32 v5, 16, v114
	v_and_b32_e32 v3, 0xffff0000, v114
	v_lshlrev_b32_e32 v6, 16, v115
	v_and_b32_e32 v7, 0xffff0000, v115
	v_lshlrev_b32_e32 v114, 16, v2
	v_and_b32_e32 v115, 0xffff0000, v2
	v_mul_f32_e32 v2, v77, v77
	v_pk_fma_f32 v[136:137], v[76:77], v[76:77], v[2:3] op_sel_hi:[1,1,0]
	v_mul_f32_e32 v2, v79, v79
	v_mul_f32_e32 v52, v70, v70
	v_mul_f32_e32 v54, v71, v71
	v_pk_fma_f32 v[138:139], v[78:79], v[78:79], v[2:3] op_sel_hi:[1,1,0]
	v_mov_b32_e32 v137, v52
	v_mov_b32_e32 v139, v54
	v_mul_f32_e32 v2, v115, v115
	v_pk_add_f32 v[136:137], v[136:137], v[138:139]
	v_pk_fma_f32 v[138:139], v[114:115], v[114:115], v[2:3] op_sel_hi:[1,1,0]
	v_mov_b32_e32 v140, v118
	v_mov_b32_e32 v74, v138
	v_mov_b32_e32 v141, v75
	v_and_b32_e32 v59, 0xffff0000, v12
	v_mul_f32_e32 v32, v73, v73
	v_pk_add_f32 v[118:119], v[138:139], v[118:119]
	v_pk_mul_f32 v[138:139], v[74:75], v[140:141]
	v_pk_add_f32 v[120:121], v[120:121], v[120:121] op_sel:[0,1] op_sel_hi:[1,0]
	v_lshlrev_b32_e32 v58, 16, v12
	v_and_b32_e32 v61, 0xffff0000, v13
	v_mov_b32_e32 v119, v139
	v_mov_b32_e32 v121, v32
	v_mul_f32_e32 v2, v59, v59
	v_lshlrev_b32_e32 v60, 16, v13
	v_lshlrev_b32_e32 v56, 16, v15
	v_and_b32_e32 v57, 0xffff0000, v15
	v_pk_add_f32 v[118:119], v[118:119], v[120:121]
	v_pk_fma_f32 v[120:121], v[58:59], v[58:59], v[2:3] op_sel_hi:[1,1,0]
	v_mul_f32_e32 v2, v61, v61
	v_mul_f32_e32 v107, v56, v56
	v_mul_f32_e32 v142, v57, v57
	v_pk_add_f32 v[118:119], v[118:119], v[136:137]
	v_pk_fma_f32 v[136:137], v[60:61], v[60:61], v[2:3] op_sel_hi:[1,1,0]
	v_lshlrev_b32_e32 v55, 16, v14
	v_pk_mul_f32 v[8:9], v[64:65], v[64:65]
	v_pk_add_f32 v[126:127], v[0:1], v[0:1] op_sel:[0,1] op_sel_hi:[1,0]
	v_mov_b32_e32 v121, v107
	v_mov_b32_e32 v137, v142
	v_pk_add_f32 v[118:119], v[118:119], v[118:119] op_sel:[0,1] op_sel_hi:[1,0]
	v_and_b32_e32 v53, 0xffff0000, v14
	v_pk_fma_f32 v[122:123], v[62:63], v[62:63], v[8:9]
	v_pk_add_f32 v[120:121], v[120:121], v[136:137]
	v_mov_b32_e32 v54, v118
	v_mov_b32_e32 v136, v126
	v_mov_b32_e32 v137, v55
	v_mul_f32_e32 v72, v53, v53
	v_pk_add_f32 v[118:119], v[118:119], v[126:127]
	v_pk_mul_f32 v[126:127], v[54:55], v[136:137]
	v_pk_add_f32 v[122:123], v[122:123], v[122:123] op_sel:[0,1] op_sel_hi:[1,0]
	v_and_b32_e32 v43, 0xffff0000, v20
	v_mov_b32_e32 v119, v127
	v_mov_b32_e32 v123, v72
	v_lshlrev_b32_e32 v42, 16, v20
	v_and_b32_e32 v47, 0xffff0000, v21
	v_pk_add_f32 v[118:119], v[118:119], v[122:123]
	v_mul_f32_e32 v2, v43, v43
	v_lshlrev_b32_e32 v46, 16, v21
	v_lshlrev_b32_e32 v34, 16, v25
	v_and_b32_e32 v35, 0xffff0000, v25
	v_pk_add_f32 v[118:119], v[118:119], v[120:121]
	v_pk_fma_f32 v[120:121], v[42:43], v[42:43], v[2:3] op_sel_hi:[1,1,0]
	v_mul_f32_e32 v2, v47, v47
	v_mul_f32_e32 v143, v34, v34
	v_mul_f32_e32 v144, v35, v35
	v_pk_fma_f32 v[122:123], v[46:47], v[46:47], v[2:3] op_sel_hi:[1,1,0]
	v_and_b32_e32 v41, 0xffff0000, v19
	v_and_b32_e32 v40, 0xffff0000, v18
; __device__ __forceinline__ float bflo(unsigned w) { return __uint_as_float(w << 16); }
; __device__ __forceinline__ float bfhi(unsigned w) { return __uint_as_float(w & 0xffff0000u); }
; #define GAS __attribute__((address_space(1)))
; #define LAS __attribute__((address_space(3)))
; __global__ void __launch_bounds__(NWAVES * 64, 2) fwd_kernel(Args args) {
;     ...
;         if (bq < 4) for (int r = wl * NWAVES + wave; r < SEQL; r += wgb * NWAVES) {
;             const int row = bq * SEQL + r; const bf16* op = OUT1 + (size_t)row * DM; float* xo = args.out + (size_t)row * DM;
;             unsigned vbase = (unsigned)lane * 16u; asm volatile("" : "+v"(vbase));
;             const LAS f32x4* Vg_ = (const LAS f32x4*)(L + vbase);
;             v2u ov[16]; float ss = 0.f;
; #pragma unroll
;             for (int j = 0; j < 16; ++j) { ov[j] = ((const GAS v2u*)op)[lane + 64 * j]; const float a = pg8::bflo(ov[j].x), b = pg8::bfhi(ov[j].x), c = pg8::bflo(ov[j].y), d = pg8::bfhi(ov[j].y); ss += (a * a + b * b) + (c * c + d * d); }
;             v2u xv[16]; const bf16* x1p = X1B + (size_t)row * DM;
; #pragma unroll
;             for (int j = 0; j < 16; ++j) xv[j] = ((const GAS v2u*)x1p)[lane + 64 * j];
;             const float rstd = __builtin_amdgcn_rsqf(wave_sum(ss) * (1.f / DM) + EPS);
; #pragma unroll
;             for (int j = 0; j < 16; ++j) { const f32x4 o4 = {pg8::bflo(ov[j].x), pg8::bfhi(ov[j].x), pg8::bflo(ov[j].y), pg8::bfhi(ov[j].y)};
;                 const f32x4 x4 = {pg8::bflo(xv[j].x), pg8::bfhi(xv[j].x), pg8::bflo(xv[j].y), pg8::bfhi(xv[j].y)};
;                 ((GAS f32x4*)xo)[lane + 64 * j] = x4 + Vg_[64 * j] * (o4 * rstd); if ((j & 3) == 3) __builtin_amdgcn_sched_barrier(0); }
;         }
	v_lshlrev_b32_e32 v33, 16, v24
	v_and_b32_e32 v31, 0xffff0000, v24
	v_and_b32_e32 v25, 0xffff0000, v109
	v_and_b32_e32 v24, 0xffff0000, v108
	v_mov_b32_e32 v121, v143
	v_mov_b32_e32 v123, v144
	v_pk_add_f32 v[118:119], v[118:119], v[118:119] op_sel:[0,1] op_sel_hi:[1,0]
	v_lshlrev_b32_e32 v39, 16, v19
	v_lshlrev_b32_e32 v38, 16, v18
	v_pk_mul_f32 v[12:13], v[40:41], v[40:41]
	v_lshlrev_b32_e32 v21, 16, v109
	v_lshlrev_b32_e32 v20, 16, v108
	v_pk_mul_f32 v[0:1], v[24:25], v[24:25]
	v_pk_add_f32 v[120:121], v[120:121], v[122:123]
	v_mov_b32_e32 v32, v118
	v_mov_b32_e32 v122, v128
	v_mov_b32_e32 v123, v33
	v_pk_fma_f32 v[124:125], v[38:39], v[38:39], v[12:13]
	v_pk_fma_f32 v[0:1], v[20:21], v[20:21], v[0:1]
	v_and_b32_e32 v19, 0xffff0000, v111
	v_and_b32_e32 v18, 0xffff0000, v110
	v_pk_add_f32 v[118:119], v[118:119], v[128:129]
	v_pk_mul_f32 v[122:123], v[32:33], v[122:123]
	v_mul_f32_e32 v4, v31, v31
	v_pk_add_f32 v[108:109], v[0:1], v[0:1] op_sel:[0,1] op_sel_hi:[1,0]
	v_lshlrev_b32_e32 v17, 16, v111
	v_lshlrev_b32_e32 v16, 16, v110
	v_pk_mul_f32 v[0:1], v[18:19], v[18:19]
	v_mov_b32_e32 v119, v123
	v_pk_add_f32 v[122:123], v[124:125], v[124:125] op_sel:[0,1] op_sel_hi:[1,0]
	global_load_dwordx2 v[14:15], v91, s[2:3] nt
	global_load_dwordx2 v[26:27], v90, s[2:3] nt
	v_pk_fma_f32 v[110:111], v[16:17], v[16:17], v[0:1]
	global_load_dwordx2 v[0:1], v93, s[2:3] nt
	global_load_dwordx2 v[10:11], v92, s[2:3] nt
	v_lshlrev_b32_e32 v8, 16, v112
	v_and_b32_e32 v9, 0xffff0000, v112
	v_lshlrev_b32_e32 v12, 16, v113
	v_and_b32_e32 v13, 0xffff0000, v113
	global_load_dwordx2 v[112:113], v85, s[2:3] nt
	global_load_dwordx2 v[130:131], v85, s[2:3] offset:512 nt
	global_load_dwordx2 v[132:133], v85, s[2:3] offset:1024 nt
	global_load_dwordx2 v[134:135], v85, s[2:3] offset:1536 nt
	v_mov_b32_e32 v123, v4
	v_pk_add_f32 v[118:119], v[118:119], v[122:123]
	v_mul_f32_e32 v2, v9, v9
	v_pk_add_f32 v[118:119], v[118:119], v[120:121]
	v_pk_fma_f32 v[120:121], v[8:9], v[8:9], v[2:3] op_sel_hi:[1,1,0]
	v_mul_f32_e32 v2, v13, v13
	v_mul_f32_e32 v146, v6, v6
	v_mul_f32_e32 v147, v7, v7
	v_pk_fma_f32 v[122:123], v[12:13], v[12:13], v[2:3] op_sel_hi:[1,1,0]
	v_mov_b32_e32 v121, v146
	v_mov_b32_e32 v123, v147
	v_pk_add_f32 v[118:119], v[118:119], v[118:119] op_sel:[0,1] op_sel_hi:[1,0]
	v_pk_add_f32 v[120:121], v[120:121], v[122:123]
	v_mov_b32_e32 v4, v118
	v_mov_b32_e32 v122, v108
	v_mov_b32_e32 v123, v5
	v_mul_f32_e32 v145, v3, v3
	v_pk_add_f32 v[108:109], v[118:119], v[108:109]
	v_pk_mul_f32 v[118:119], v[4:5], v[122:123]
	v_pk_add_f32 v[110:111], v[110:111], v[110:111] op_sel:[0,1] op_sel_hi:[1,0]
	v_mov_b32_e32 v109, v119
	v_mov_b32_e32 v111, v145
	v_pk_add_f32 v[108:109], v[108:109], v[110:111]
	v_add_u32_e32 v107, 0, v30
	v_pk_add_f32 v[108:109], v[108:109], v[120:121]
	global_load_dwordx2 v[118:119], v85, s[2:3] offset:2048 nt
	global_load_dwordx2 v[120:121], v85, s[2:3] offset:2560 nt
	global_load_dwordx2 v[122:123], v85, s[2:3] offset:3072 nt
	global_load_dwordx2 v[124:125], v85, s[2:3] offset:3584 nt
	v_add_f32_e32 v2, v108, v109
	ds_bpermute_b32 v4, v210, v2
	ds_read_b128 v[108:111], v107
	v_mov_b32_e32 v72, v75
	s_waitcnt lgkmcnt(1)
	v_add_f32_e32 v2, v2, v4
	ds_bpermute_b32 v4, v211, v2
	s_waitcnt lgkmcnt(0)
	v_add_f32_e32 v2, v2, v4
	ds_bpermute_b32 v4, v212, v2
	s_waitcnt lgkmcnt(0)
	v_add_f32_e32 v2, v2, v4
	ds_bpermute_b32 v4, v213, v2
	s_waitcnt lgkmcnt(0)
	v_add_f32_e32 v2, v2, v4
	ds_bpermute_b32 v4, v214, v2
	s_waitcnt lgkmcnt(0)
	v_add_f32_e32 v2, v2, v4
	ds_bpermute_b32 v4, v215, v2
	s_waitcnt lgkmcnt(0)
	v_add_f32_e32 v2, v2, v4
	v_fmamk_f32 v2, v2, 0x39800000, v94
	v_rsq_f32_e32 v4, v2
	s_waitcnt vmcnt(7)
	v_lshlrev_b32_e32 v126, 16, v112
	v_and_b32_e32 v127, 0xffff0000, v112
	v_lshlrev_b32_e32 v128, 16, v113
	v_and_b32_e32 v129, 0xffff0000, v113
	v_pk_mul_f32 v[136:137], v[4:5], v[114:115] op_sel_hi:[0,1]
	ds_read_b128 v[112:115], v107 offset:1024
	v_pk_mul_f32 v[116:117], v[4:5], v[116:117] op_sel_hi:[0,1]
	v_pk_fma_f32 v[110:111], v[110:111], v[116:117], v[128:129]
	v_pk_fma_f32 v[108:109], v[108:109], v[136:137], v[126:127]
	v_mov_b32_e32 v116, v82
	v_mov_b32_e32 v117, v80
	v_mov_b32_e32 v80, v83
	global_store_dwordx4 v84, v[108:111], s[0:1] nt
	v_pk_mul_f32 v[116:117], v[4:5], v[116:117] op_sel_hi:[0,1]
	v_pk_mul_f32 v[80:81], v[4:5], v[80:81] op_sel_hi:[0,1]
	s_waitcnt vmcnt(7)
	v_lshlrev_b32_e32 v108, 16, v130
	v_and_b32_e32 v109, 0xffff0000, v130
	v_lshlrev_b32_e32 v110, 16, v131
	v_and_b32_e32 v111, 0xffff0000, v131
	s_waitcnt lgkmcnt(0)
	v_pk_fma_f32 v[82:83], v[114:115], v[80:81], v[110:111]
	v_pk_fma_f32 v[80:81], v[112:113], v[116:117], v[108:109]
	global_store_dwordx4 v84, v[80:83], s[0:1] offset:1024 nt
	ds_read_b128 v[80:83], v107 offset:2048
	v_pk_mul_f32 v[112:113], v[4:5], v[76:77] op_sel_hi:[0,1]
	v_pk_mul_f32 v[114:115], v[4:5], v[78:79] op_sel_hi:[0,1]
	ds_read_b128 v[76:79], v107 offset:3072
	s_waitcnt vmcnt(7)
	v_lshlrev_b32_e32 v108, 16, v132
	v_and_b32_e32 v109, 0xffff0000, v132
	v_lshlrev_b32_e32 v110, 16, v133
	v_and_b32_e32 v111, 0xffff0000, v133
	s_waitcnt lgkmcnt(1)
	v_pk_fma_f32 v[82:83], v[82:83], v[114:115], v[110:111]
	v_pk_fma_f32 v[80:81], v[80:81], v[112:113], v[108:109]
	global_store_dwordx4 v84, v[80:83], s[0:1] offset:2048 nt
	v_pk_mul_f32 v[74:75], v[4:5], v[72:73] op_sel_hi:[0,1]
	v_pk_mul_f32 v[70:71], v[4:5], v[70:71] op_sel_hi:[0,1]
	s_waitcnt vmcnt(7)
	v_lshlrev_b32_e32 v80, 16, v134
	v_and_b32_e32 v81, 0xffff0000, v134
	v_lshlrev_b32_e32 v82, 16, v135
	v_and_b32_e32 v83, 0xffff0000, v135
	s_waitcnt lgkmcnt(0)
; __device__ __forceinline__ float bflo(unsigned w) { return __uint_as_float(w << 16); }
; __device__ __forceinline__ float bfhi(unsigned w) { return __uint_as_float(w & 0xffff0000u); }
; #define GAS __attribute__((address_space(1)))
; #define LAS __attribute__((address_space(3)))
; __global__ void __launch_bounds__(NWAVES * 64, 2) fwd_kernel(Args args) {
;     ...
;         if (bq < 4) for (int r = wl * NWAVES + wave; r < SEQL; r += wgb * NWAVES) {
;             const int row = bq * SEQL + r; const bf16* op = OUT1 + (size_t)row * DM; float* xo = args.out + (size_t)row * DM;
;             unsigned vbase = (unsigned)lane * 16u; asm volatile("" : "+v"(vbase));
;             const LAS f32x4* Vg_ = (const LAS f32x4*)(L + vbase);
;             v2u ov[16]; float ss = 0.f;
; #pragma unroll
;             for (int j = 0; j < 16; ++j) { ov[j] = ((const GAS v2u*)op)[lane + 64 * j]; const float a = pg8::bflo(ov[j].x), b = pg8::bfhi(ov[j].x), c = pg8::bflo(ov[j].y), d = pg8::bfhi(ov[j].y); ss += (a * a + b * b) + (c * c + d * d); }
;             v2u xv[16]; const bf16* x1p = X1B + (size_t)row * DM;
; #pragma unroll
;             for (int j = 0; j < 16; ++j) xv[j] = ((const GAS v2u*)x1p)[lane + 64 * j];
;             const float rstd = __builtin_amdgcn_rsqf(wave_sum(ss) * (1.f / DM) + EPS);
; #pragma unroll
;             for (int j = 0; j < 16; ++j) { const f32x4 o4 = {pg8::bflo(ov[j].x), pg8::bfhi(ov[j].x), pg8::bflo(ov[j].y), pg8::bfhi(ov[j].y)};
;                 const f32x4 x4 = {pg8::bflo(xv[j].x), pg8::bfhi(xv[j].x), pg8::bflo(xv[j].y), pg8::bfhi(xv[j].y)};
;                 ((GAS f32x4*)xo)[lane + 64 * j] = x4 + Vg_[64 * j] * (o4 * rstd); if ((j & 3) == 3) __builtin_amdgcn_sched_barrier(0); }
;         }
	v_pk_fma_f32 v[72:73], v[78:79], v[70:71], v[82:83]
	v_pk_fma_f32 v[70:71], v[76:77], v[74:75], v[80:81]
	global_store_dwordx4 v84, v[70:73], s[0:1] offset:3072 nt
	ds_read_b128 v[70:73], v107 offset:4096
	v_mov_b32_e32 v78, v67
	v_mov_b32_e32 v67, v68
	v_mov_b32_e32 v79, v69
	v_pk_mul_f32 v[80:81], v[4:5], v[66:67] op_sel_hi:[0,1]
	ds_read_b128 v[66:69], v107 offset:5120
	s_waitcnt vmcnt(7)
	v_lshlrev_b32_e32 v74, 16, v118
	v_and_b32_e32 v75, 0xffff0000, v118
	v_lshlrev_b32_e32 v76, 16, v119
	v_and_b32_e32 v77, 0xffff0000, v119
	v_pk_mul_f32 v[78:79], v[4:5], v[78:79] op_sel_hi:[0,1]
	s_waitcnt lgkmcnt(1)
	v_pk_fma_f32 v[70:71], v[70:71], v[80:81], v[74:75]
	v_pk_fma_f32 v[72:73], v[72:73], v[78:79], v[76:77]
	v_mov_b32_e32 v74, v63
	v_mov_b32_e32 v75, v65
	v_mov_b32_e32 v63, v64
	global_store_dwordx4 v95, v[70:73], s[0:1] nt
	v_pk_mul_f32 v[74:75], v[4:5], v[74:75] op_sel_hi:[0,1]
	v_pk_mul_f32 v[62:63], v[4:5], v[62:63] op_sel_hi:[0,1]
	s_waitcnt vmcnt(7)
	v_lshlrev_b32_e32 v70, 16, v120
	v_and_b32_e32 v71, 0xffff0000, v120
	v_lshlrev_b32_e32 v72, 16, v121
	v_and_b32_e32 v73, 0xffff0000, v121
	s_waitcnt lgkmcnt(0)
	v_pk_fma_f32 v[62:63], v[66:67], v[62:63], v[70:71]
	v_pk_fma_f32 v[64:65], v[68:69], v[74:75], v[72:73]
	global_store_dwordx4 v96, v[62:65], s[0:1] nt
	ds_read_b128 v[62:65], v107 offset:6144
	v_pk_mul_f32 v[70:71], v[4:5], v[60:61] op_sel_hi:[0,1]
	v_pk_mul_f32 v[72:73], v[4:5], v[58:59] op_sel_hi:[0,1]
	ds_read_b128 v[58:61], v107 offset:7168
	s_waitcnt vmcnt(7)
	v_lshlrev_b32_e32 v66, 16, v122
	v_and_b32_e32 v67, 0xffff0000, v122
	v_lshlrev_b32_e32 v68, 16, v123
	v_and_b32_e32 v69, 0xffff0000, v123
	s_waitcnt lgkmcnt(1)
	v_pk_fma_f32 v[62:63], v[62:63], v[72:73], v[66:67]
	v_pk_fma_f32 v[64:65], v[64:65], v[70:71], v[68:69]
	v_mov_b32_e32 v52, v55
	global_store_dwordx4 v97, v[62:65], s[0:1] nt
	v_pk_mul_f32 v[56:57], v[4:5], v[56:57] op_sel_hi:[0,1]
	v_pk_mul_f32 v[52:53], v[4:5], v[52:53] op_sel_hi:[0,1]
	s_waitcnt vmcnt(7)
	v_lshlrev_b32_e32 v62, 16, v124
	v_and_b32_e32 v63, 0xffff0000, v124
	v_lshlrev_b32_e32 v64, 16, v125
	v_and_b32_e32 v65, 0xffff0000, v125
	s_waitcnt lgkmcnt(0)
	v_pk_fma_f32 v[52:53], v[58:59], v[52:53], v[62:63]
	v_pk_fma_f32 v[54:55], v[60:61], v[56:57], v[64:65]
	global_store_dwordx4 v98, v[52:55], s[0:1] nt
	ds_read_b128 v[52:55], v107 offset:8192
	v_mov_b32_e32 v58, v49
	v_mov_b32_e32 v49, v50
	v_mov_b32_e32 v59, v51
	v_pk_mul_f32 v[60:61], v[4:5], v[48:49] op_sel_hi:[0,1]
	ds_read_b128 v[48:51], v107 offset:9216
	v_lshlrev_b32_e32 v56, 16, v36
	v_and_b32_e32 v57, 0xffff0000, v36
	v_lshlrev_b32_e32 v36, 16, v37
	v_and_b32_e32 v37, 0xffff0000, v37
	v_pk_mul_f32 v[58:59], v[4:5], v[58:59] op_sel_hi:[0,1]
	s_waitcnt lgkmcnt(1)
	v_pk_fma_f32 v[52:53], v[52:53], v[60:61], v[56:57]
	v_pk_fma_f32 v[54:55], v[54:55], v[58:59], v[36:37]
	global_store_dwordx4 v99, v[52:55], s[0:1] nt
	v_lshlrev_b32_e32 v36, 16, v22
	v_and_b32_e32 v37, 0xffff0000, v22
	v_mov_b32_e32 v52, v39
	v_mov_b32_e32 v53, v41
	v_mov_b32_e32 v39, v40
	v_lshlrev_b32_e32 v22, 16, v23
	v_and_b32_e32 v23, 0xffff0000, v23
	v_pk_mul_f32 v[52:53], v[4:5], v[52:53] op_sel_hi:[0,1]
	v_pk_mul_f32 v[38:39], v[4:5], v[38:39] op_sel_hi:[0,1]
	s_waitcnt lgkmcnt(0)
	v_pk_fma_f32 v[36:37], v[48:49], v[38:39], v[36:37]
	v_pk_fma_f32 v[38:39], v[50:51], v[52:53], v[22:23]
	global_store_dwordx4 v100, v[36:39], s[0:1] nt
	ds_read_b128 v[36:39], v107 offset:10240
	v_pk_mul_f32 v[48:49], v[4:5], v[42:43] op_sel_hi:[0,1]
	ds_read_b128 v[40:43], v107 offset:11264
	v_lshlrev_b32_e32 v22, 16, v44
	v_and_b32_e32 v23, 0xffff0000, v44
	v_lshlrev_b32_e32 v44, 16, v45
	v_and_b32_e32 v45, 0xffff0000, v45
	v_pk_mul_f32 v[46:47], v[4:5], v[46:47] op_sel_hi:[0,1]
	s_waitcnt lgkmcnt(1)
	v_pk_fma_f32 v[36:37], v[36:37], v[48:49], v[22:23]
	v_pk_fma_f32 v[38:39], v[38:39], v[46:47], v[44:45]
	v_mov_b32_e32 v30, v33
	global_store_dwordx4 v101, v[36:39], s[0:1] nt
	v_lshlrev_b32_e32 v22, 16, v28
	v_and_b32_e32 v23, 0xffff0000, v28
	v_lshlrev_b32_e32 v36, 16, v29
	v_and_b32_e32 v37, 0xffff0000, v29
	v_pk_mul_f32 v[34:35], v[4:5], v[34:35] op_sel_hi:[0,1]
	v_pk_mul_f32 v[28:29], v[4:5], v[30:31] op_sel_hi:[0,1]
	s_waitcnt lgkmcnt(0)
	v_pk_fma_f32 v[28:29], v[40:41], v[28:29], v[22:23]
	v_pk_fma_f32 v[30:31], v[42:43], v[34:35], v[36:37]
	global_store_dwordx4 v102, v[28:31], s[0:1] nt
	s_nop 1
	v_lshlrev_b32_e32 v30, 16, v26
	v_and_b32_e32 v31, 0xffff0000, v26
	v_lshlrev_b32_e32 v32, 16, v27
	v_and_b32_e32 v33, 0xffff0000, v27
	ds_read_b128 v[26:29], v107 offset:12288
	v_mov_b32_e32 v22, v21
	v_mov_b32_e32 v23, v25
	v_mov_b32_e32 v21, v24
	v_pk_mul_f32 v[34:35], v[4:5], v[22:23] op_sel_hi:[0,1]
	v_pk_mul_f32 v[24:25], v[4:5], v[20:21] op_sel_hi:[0,1]
	ds_read_b128 v[20:23], v107 offset:13312
	s_waitcnt lgkmcnt(1)
	v_pk_fma_f32 v[24:25], v[26:27], v[24:25], v[30:31]
	v_pk_fma_f32 v[26:27], v[28:29], v[34:35], v[32:33]
	global_store_dwordx4 v103, v[24:27], s[0:1] nt
	v_mov_b32_e32 v2, v5
	v_pk_mul_f32 v[6:7], v[4:5], v[6:7] op_sel_hi:[0,1]
	v_lshlrev_b32_e32 v24, 16, v14
	v_and_b32_e32 v25, 0xffff0000, v14
	v_lshlrev_b32_e32 v26, 16, v15
	v_and_b32_e32 v27, 0xffff0000, v15
	v_mov_b32_e32 v14, v17
	v_mov_b32_e32 v15, v19
	v_mov_b32_e32 v17, v18
	v_pk_mul_f32 v[28:29], v[4:5], v[14:15] op_sel_hi:[0,1]
	v_pk_mul_f32 v[14:15], v[4:5], v[16:17] op_sel_hi:[0,1]
	s_waitcnt lgkmcnt(0)
	v_pk_fma_f32 v[14:15], v[20:21], v[14:15], v[24:25]
	v_pk_fma_f32 v[16:17], v[22:23], v[28:29], v[26:27]
	global_store_dwordx4 v104, v[14:17], s[0:1] nt
	ds_read_b128 v[14:17], v107 offset:14336
	v_lshlrev_b32_e32 v18, 16, v10
	v_and_b32_e32 v19, 0xffff0000, v10
	v_lshlrev_b32_e32 v20, 16, v11
	v_and_b32_e32 v21, 0xffff0000, v11
	v_pk_mul_f32 v[22:23], v[4:5], v[12:13] op_sel_hi:[0,1]
	v_pk_mul_f32 v[12:13], v[4:5], v[8:9] op_sel_hi:[0,1]
	ds_read_b128 v[8:11], v107 offset:15360
	s_waitcnt lgkmcnt(1)
	v_pk_fma_f32 v[12:13], v[14:15], v[12:13], v[18:19]
	v_pk_fma_f32 v[14:15], v[16:17], v[22:23], v[20:21]
	global_store_dwordx4 v105, v[12:15], s[0:1] nt
	s_nop 1
	v_lshlrev_b32_e32 v12, 16, v0
	v_and_b32_e32 v13, 0xffff0000, v0
	v_lshlrev_b32_e32 v14, 16, v1
	v_and_b32_e32 v15, 0xffff0000, v1
	v_pk_mul_f32 v[0:1], v[4:5], v[2:3] op_sel_hi:[0,1]
	s_waitcnt lgkmcnt(0)
	v_pk_fma_f32 v[0:1], v[8:9], v[0:1], v[12:13]
	v_pk_fma_f32 v[2:3], v[10:11], v[6:7], v[14:15]
	global_store_dwordx4 v106, v[0:3], s[0:1] nt
	s_add_i32 s6, s6, s8
	s_cmpk_lt_i32 s6, 0x1000
	s_cbranch_scc1 .LBB0_1335

; __global__ void __launch_bounds__(NWAVES * 64, 2) fwd_kernel(Args args) {
	.amdhsa_kernel _Z10fwd_kernel4Args
		.amdhsa_group_segment_fixed_size 0
		.amdhsa_private_segment_fixed_size 0
		.amdhsa_kernarg_size 464
		.amdhsa_user_sgpr_count 2
		.amdhsa_user_sgpr_dispatch_ptr 0
		.amdhsa_user_sgpr_queue_ptr 0
		.amdhsa_user_sgpr_kernarg_segment_ptr 1
		.amdhsa_user_sgpr_dispatch_id 0
		.amdhsa_user_sgpr_kernarg_preload_length 0
		.amdhsa_user_sgpr_kernarg_preload_offset 0
		.amdhsa_user_sgpr_private_segment_size 0
		.amdhsa_uses_dynamic_stack 0
		.amdhsa_enable_private_segment 0
		.amdhsa_system_sgpr_workgroup_id_x 1
		.amdhsa_system_sgpr_workgroup_id_y 0
		.amdhsa_system_sgpr_workgroup_id_z 0
		.amdhsa_system_sgpr_workgroup_info 0
		.amdhsa_system_vgpr_workitem_id 0
		.amdhsa_next_free_vgpr 256
		.amdhsa_next_free_sgpr 102
		.amdhsa_accum_offset 256
		.amdhsa_reserve_vcc 1
		.amdhsa_float_round_mode_32 0
		.amdhsa_float_round_mode_16_64 0
		.amdhsa_float_denorm_mode_32 3
		.amdhsa_float_denorm_mode_16_64 3
		.amdhsa_dx10_clamp 1
		.amdhsa_ieee_mode 1
		.amdhsa_fp16_overflow 0
		.amdhsa_tg_split 0
		.amdhsa_exception_fp_ieee_invalid_op 0
		.amdhsa_exception_fp_denorm_src 0
		.amdhsa_exception_fp_ieee_div_zero 0
		.amdhsa_exception_fp_ieee_overflow 0
		.amdhsa_exception_fp_ieee_underflow 0
		.amdhsa_exception_fp_ieee_inexact 0
		.amdhsa_exception_int_div_zero 0
	.end_amdhsa_kernel

; __global__ void __launch_bounds__(NWAVES * 64, 2) fwd_kernel(Args args) {
amdhsa.kernels:
  - .agpr_count:     0
    .args:
      - .offset:         0
        .size:           208
        .value_kind:     by_value
      - .offset:         208
        .size:           4
        .value_kind:     hidden_block_count_x
      - .offset:         212
        .size:           4
        .value_kind:     hidden_block_count_y
      - .offset:         216
        .size:           4
        .value_kind:     hidden_block_count_z
      - .offset:         220
        .size:           2
        .value_kind:     hidden_group_size_x
      - .offset:         222
        .size:           2
        .value_kind:     hidden_group_size_y
      - .offset:         224
        .size:           2
        .value_kind:     hidden_group_size_z
      - .offset:         226
        .size:           2
        .value_kind:     hidden_remainder_x
      - .offset:         228
        .size:           2
        .value_kind:     hidden_remainder_y
      - .offset:         230
        .size:           2
        .value_kind:     hidden_remainder_z
      - .offset:         248
        .size:           8
        .value_kind:     hidden_global_offset_x
      - .offset:         256
        .size:           8
        .value_kind:     hidden_global_offset_y
      - .offset:         264
        .size:           8
        .value_kind:     hidden_global_offset_z
      - .offset:         272
        .size:           2
        .value_kind:     hidden_grid_dims
      - .offset:         328
        .size:           4
        .value_kind:     hidden_dynamic_lds_size
    .group_segment_fixed_size: 0
    .kernarg_segment_align: 8
    .kernarg_segment_size: 464
    .language:       OpenCL C
    .language_version:
      - 2
      - 0
    .max_flat_workgroup_size: 512
    .name:           _Z10fwd_kernel4Args
    .private_segment_fixed_size: 0
    .sgpr_count:     108
    .sgpr_spill_count: 115
    .symbol:         _Z10fwd_kernel4Args.kd
    .uniform_work_group_size: 1
    .uses_dynamic_stack: false
    .vgpr_count:     256
    .vgpr_spill_count: 0
    .wavefront_size: 64
